# v66 + G1 epilogue writes full 512-byte rows through an LDS staging area (write-through) instead of 64-byte pieces
# baseline (speedup 1.0000x reference)
; #define LAS __attribute__((address_space(3)))
; __host__ __device__ __forceinline__ unsigned img_off(unsigned row, unsigned col, unsigned KT) { return (((row >> 8) * KT + (col >> 6)) << 14) + (((row >> 7) & 1u) << 13) + hl_off(row & 127u, col & 63u); }
; __device__ __forceinline__ unsigned cvt_pk_bf16(float lo, float hi) { unsigned r; asm volatile("v_cvt_pk_bf16_f32 %0, %1, %2" : "=v"(r) : "v"(lo), "v"(hi)); return r; }
;     __device__ __forceinline__ void operator()(const f32x4 (&acc)[2][2][4][2], const Unit& u, int wr, int wc, int fr, int fq, const LAS float* pre) const {
;         const int col0 = u.pn * BM + wc * 32 + 8 * fq;
;         f32x4 sv[2][2];
; #pragma unroll
;         for (int bj = 0; bj < 2; ++bj)
; #pragma unroll
;             for (int n = 0; n < 2; ++n) sv[bj][n] = *(const LAS f32x4*)(pre + 256 + wc * 32 + 8 * fq + bj * HALF + 4 * n);
;         float rsv[2][4];
; #pragma unroll
;         for (int ai = 0; ai < 2; ++ai)
; #pragma unroll
;             for (int m = 0; m < 4; ++m) rsv[ai][m] = pre[ai * HALF + wr * 64 + m * 16 + fr];
;         store(acc, u, wr, wc, fr, fq, col0, sv, rsv);
;     __device__ __forceinline__ void store(const f32x4 (&acc)[2][2][4][2], const Unit& u, int wr, int wc, int fr, int fq, int col0, const f32x4 (&sv)[2][2], const float (&rsv)[2][4]) const {
; #pragma unroll
;         for (int ai = 0; ai < 2; ++ai)
; #pragma unroll
;             for (int m = 0; m < 4; ++m) {
;                 const int row = u.pm * BM + ai * HALF + wr * 64 + m * 16 + fr;
;                 const float rs = rsv[ai][m];
;                 bf16_t* rowp = TILED ? O + img_off((unsigned)row, (unsigned)col0, (unsigned)(ldc >> 6)) : O + (size_t)row * ldc + col0;
; #pragma unroll
;                 for (int bj = 0; bj < 2; ++bj) {
;                     f32x4 v0 = acc[ai][bj][m][0] * rs + sv[bj][0], v1 = acc[ai][bj][m][1] * rs + sv[bj][1];
;                     if (ACT == 1) {
; #pragma unroll
;                         for (int e = 0; e < 4; ++e) { const float a0 = fmaxf(v0[e], 0.f), a1 = fmaxf(v1[e], 0.f); v0[e] = a0 * a0; v1[e] = a1 * a1; }
;                     }
;                     u32x4 w; w.x = cvt_pk_bf16(v0[0], v0[1]); w.y = cvt_pk_bf16(v0[2], v0[3]); w.z = cvt_pk_bf16(v1[0], v1[1]); w.w = cvt_pk_bf16(v1[2], v1[3]);
;                     *(u32x4*)(rowp + (TILED ? bj * 2 * (256 * 64) : bj * HALF)) = w;
;                 }
.LBB0_897:
	s_lshl_b32 s34, s78, 11
	s_add_i32 s34, s34, 0
	s_add_i32 s34, s34, 0x20000
	s_lshl_b32 s35, s74, 2
	s_add_i32 s35, s34, s35
	s_add_i32 s34, s34, s77
	v_readlane_b32 s28, v254, 59
	v_lshl_add_u32 v130, v171, 2, s35
	v_lshl_add_u32 v146, v167, 2, s34
	s_lshl_b32 s34, s38, 8
	v_readlane_b32 s29, v254, 60
	s_nop 3
	s_mul_i32 s98, s34, 0xe00
	s_lshl_b32 s99, s4, 9
	s_add_u32 s98, s98, s99
	s_add_u32 s98, s98, s28
	s_addc_u32 s99, s29, 0
	v_and_b32_e32 v190, 15, v0
	v_bfe_u32 v191, v0, 4, 2
	v_lshrrev_b32_e32 v192, 6, v0
	v_and_b32_e32 v193, 3, v192
	v_lshrrev_b32_e32 v192, 2, v192
	v_mul_u32_u24_e32 v194, 0x2100, v192
	v_add_u32_e32 v194, 0x21800, v194
	v_mul_u32_u24_e32 v195, 0x210, v190
	v_lshl_add_u32 v195, v193, 6, v195
	v_lshl_add_u32 v195, v191, 4, v195
	v_add_u32_e32 v190, v194, v195
	v_bfe_u32 v195, v0, 5, 1
	v_lshl_add_u32 v195, v193, 2, v195
	v_and_b32_e32 v196, 31, v0
	v_lshlrev_b32_e32 v196, 4, v196
	v_mul_u32_u24_e32 v197, 0x210, v195
	v_add3_u32 v191, v194, v197, v196
	v_lshl_add_u32 v195, v192, 6, v195
	v_mul_u32_u24_e32 v195, 0xe00, v195
	v_add_u32_e32 v192, v195, v196
	ds_read_b128 v[142:145], v130 offset:1024
	ds_read_b128 v[138:141], v130 offset:1040
	ds_read_b128 v[134:137], v130 offset:1536
	ds_read_b128 v[130:133], v130 offset:1552
	ds_read2_b32 v[164:165], v146 offset1:16
	ds_read2_b32 v[184:185], v146 offset0:32 offset1:48
	ds_read2_b32 v[152:153], v146 offset0:128 offset1:144
	ds_read2_b32 v[146:147], v146 offset0:160 offset1:176
	v_ashrrev_i32_e32 v163, 31, v162
	v_add_u32_e32 v150, s34, v169
	v_mov_b64_e32 v[148:149], s[28:29]
	v_mad_i64_i32 v[154:155], s[52:53], v150, s24, v[148:149]
	v_lshlrev_b64 v[150:151], 1, v[162:163]
	v_lshl_add_u64 v[162:163], v[154:155], 0, v[150:151]
	s_waitcnt lgkmcnt(0)
	v_pk_fma_f32 v[154:155], v[126:127], v[164:165], v[142:143] op_sel_hi:[1,0,1]
	v_pk_fma_f32 v[156:157], v[128:129], v[164:165], v[144:145] op_sel_hi:[1,0,1]
	v_cvt_pk_bf16_f32 v154, v154, v155
	v_pk_fma_f32 v[186:187], v[124:125], v[164:165], v[140:141] op_sel_hi:[1,0,1]
	v_cvt_pk_bf16_f32 v155, v156, v157
	v_pk_fma_f32 v[188:189], v[122:123], v[164:165], v[138:139] op_sel_hi:[1,0,1]
	s_nop 0
	v_cvt_pk_bf16_f32 v156, v188, v189
	v_cvt_pk_bf16_f32 v157, v186, v187
	ds_write_b128 v190, v[154:157]
	v_pk_fma_f32 v[186:187], v[92:93], v[164:165], v[132:133] op_sel_hi:[1,0,1]
	v_pk_fma_f32 v[188:189], v[90:91], v[164:165], v[130:131] op_sel_hi:[1,0,1]
	v_pk_fma_f32 v[154:155], v[94:95], v[164:165], v[134:135] op_sel_hi:[1,0,1]
	v_pk_fma_f32 v[156:157], v[96:97], v[164:165], v[136:137] op_sel_hi:[1,0,1]
	v_cvt_pk_bf16_f32 v154, v154, v155
	v_mov_b32_e32 v164, v165
	v_cvt_pk_bf16_f32 v155, v156, v157
	v_cvt_pk_bf16_f32 v156, v188, v189
	v_cvt_pk_bf16_f32 v157, v186, v187
	ds_write_b128 v190, v[154:157] offset:256
	s_waitcnt lgkmcnt(0)
	s_barrier
	ds_read_b128 v[194:197], v191
	ds_read_b128 v[198:201], v191 offset:1056
	v_add_u32_e32 v193, 0x0, v192
	v_add_u32_e32 v202, 0x1c00, v192
	s_waitcnt lgkmcnt(1)
	global_store_dwordx4 v193, v[194:197], s[98:99] sc0 sc1
	s_waitcnt lgkmcnt(0)
	global_store_dwordx4 v202, v[198:201], s[98:99] sc0 sc1
	s_barrier
	v_pk_fma_f32 v[186:187], v[116:117], v[164:165], v[140:141] op_sel_hi:[1,0,1]
	v_pk_fma_f32 v[188:189], v[114:115], v[164:165], v[138:139] op_sel_hi:[1,0,1]
	v_add_u32_e32 v154, s34, v175
	v_mad_i64_i32 v[154:155], s[52:53], v154, s24, v[148:149]
	v_lshl_add_u64 v[162:163], v[154:155], 0, v[150:151]
	v_pk_fma_f32 v[154:155], v[118:119], v[164:165], v[142:143] op_sel_hi:[1,0,1]
	v_pk_fma_f32 v[156:157], v[120:121], v[164:165], v[144:145] op_sel_hi:[1,0,1]
	v_cvt_pk_bf16_f32 v154, v154, v155
	s_nop 0
	v_cvt_pk_bf16_f32 v155, v156, v157
	v_cvt_pk_bf16_f32 v156, v188, v189
	v_cvt_pk_bf16_f32 v157, v186, v187
	ds_write_b128 v190, v[154:157]
	v_pk_fma_f32 v[186:187], v[84:85], v[164:165], v[132:133] op_sel_hi:[1,0,1]
	s_nop 0
	v_pk_fma_f32 v[154:155], v[86:87], v[164:165], v[134:135] op_sel_hi:[1,0,1]
	v_pk_fma_f32 v[156:157], v[88:89], v[164:165], v[136:137] op_sel_hi:[1,0,1]
	v_cvt_pk_bf16_f32 v154, v154, v155
	v_pk_fma_f32 v[164:165], v[82:83], v[164:165], v[130:131] op_sel_hi:[1,0,1]
	v_cvt_pk_bf16_f32 v155, v156, v157
	s_nop 0
	v_cvt_pk_bf16_f32 v156, v164, v165
	v_cvt_pk_bf16_f32 v157, v186, v187
	ds_write_b128 v190, v[154:157] offset:256
	s_waitcnt lgkmcnt(0)
	s_barrier
	ds_read_b128 v[194:197], v191
	ds_read_b128 v[198:201], v191 offset:1056
	v_add_u32_e32 v193, 0xe000, v192
	v_add_u32_e32 v202, 0xfc00, v192
	s_waitcnt lgkmcnt(1)
	global_store_dwordx4 v193, v[194:197], s[98:99] sc0 sc1
	s_waitcnt lgkmcnt(0)
	global_store_dwordx4 v202, v[198:201], s[98:99] sc0 sc1
	s_barrier
	v_pk_fma_f32 v[164:165], v[108:109], v[184:185], v[140:141] op_sel_hi:[1,0,1]
	v_pk_fma_f32 v[186:187], v[106:107], v[184:185], v[138:139] op_sel_hi:[1,0,1]
	v_add_u32_e32 v154, s34, v176
	v_mad_i64_i32 v[154:155], s[52:53], v154, s24, v[148:149]
	v_lshl_add_u64 v[162:163], v[154:155], 0, v[150:151]
	v_pk_fma_f32 v[154:155], v[110:111], v[184:185], v[142:143] op_sel_hi:[1,0,1]
	v_pk_fma_f32 v[156:157], v[112:113], v[184:185], v[144:145] op_sel_hi:[1,0,1]
	v_cvt_pk_bf16_f32 v154, v154, v155
	s_nop 0
	v_cvt_pk_bf16_f32 v155, v156, v157
	v_cvt_pk_bf16_f32 v156, v186, v187
	v_cvt_pk_bf16_f32 v157, v164, v165
	ds_write_b128 v190, v[154:157]
	v_pk_fma_f32 v[164:165], v[76:77], v[184:185], v[132:133] op_sel_hi:[1,0,1]
	v_pk_fma_f32 v[186:187], v[74:75], v[184:185], v[130:131] op_sel_hi:[1,0,1]
	v_pk_fma_f32 v[154:155], v[78:79], v[184:185], v[134:135] op_sel_hi:[1,0,1]
	v_pk_fma_f32 v[156:157], v[80:81], v[184:185], v[136:137] op_sel_hi:[1,0,1]
	v_cvt_pk_bf16_f32 v154, v154, v155
	s_nop 0
	v_cvt_pk_bf16_f32 v155, v156, v157
	v_cvt_pk_bf16_f32 v156, v186, v187
	v_cvt_pk_bf16_f32 v157, v164, v165
	ds_write_b128 v190, v[154:157] offset:256
	s_waitcnt lgkmcnt(0)
	s_barrier
; __host__ __device__ __forceinline__ unsigned img_off(unsigned row, unsigned col, unsigned KT) { return (((row >> 8) * KT + (col >> 6)) << 14) + (((row >> 7) & 1u) << 13) + hl_off(row & 127u, col & 63u); }
; __device__ __forceinline__ unsigned cvt_pk_bf16(float lo, float hi) { unsigned r; asm volatile("v_cvt_pk_bf16_f32 %0, %1, %2" : "=v"(r) : "v"(lo), "v"(hi)); return r; }
;     __device__ __forceinline__ void store(const f32x4 (&acc)[2][2][4][2], const Unit& u, int wr, int wc, int fr, int fq, int col0, const f32x4 (&sv)[2][2], const float (&rsv)[2][4]) const {
;     ...
;         for (int ai = 0; ai < 2; ++ai)
; #pragma unroll
;             for (int m = 0; m < 4; ++m) {
;                 const int row = u.pm * BM + ai * HALF + wr * 64 + m * 16 + fr;
;                 const float rs = rsv[ai][m];
;                 bf16_t* rowp = TILED ? O + img_off((unsigned)row, (unsigned)col0, (unsigned)(ldc >> 6)) : O + (size_t)row * ldc + col0;
; #pragma unroll
;                 for (int bj = 0; bj < 2; ++bj) {
;                     f32x4 v0 = acc[ai][bj][m][0] * rs + sv[bj][0], v1 = acc[ai][bj][m][1] * rs + sv[bj][1];
;                     if (ACT == 1) {
; #pragma unroll
;                         for (int e = 0; e < 4; ++e) { const float a0 = fmaxf(v0[e], 0.f), a1 = fmaxf(v1[e], 0.f); v0[e] = a0 * a0; v1[e] = a1 * a1; }
;                     }
;                     u32x4 w; w.x = cvt_pk_bf16(v0[0], v0[1]); w.y = cvt_pk_bf16(v0[2], v0[3]); w.z = cvt_pk_bf16(v1[0], v1[1]); w.w = cvt_pk_bf16(v1[2], v1[3]);
;                     *(u32x4*)(rowp + (TILED ? bj * 2 * (256 * 64) : bj * HALF)) = w;
;                 }
	ds_read_b128 v[194:197], v191
	ds_read_b128 v[198:201], v191 offset:1056
	v_add_u32_e32 v193, 0x1c000, v192
	v_add_u32_e32 v202, 0x1dc00, v192
	s_waitcnt lgkmcnt(1)
	global_store_dwordx4 v193, v[194:197], s[98:99] sc0 sc1
	s_waitcnt lgkmcnt(0)
	global_store_dwordx4 v202, v[198:201], s[98:99] sc0 sc1
	s_barrier
	v_mov_b32_e32 v164, v185
	v_pk_fma_f32 v[184:185], v[100:101], v[164:165], v[140:141] op_sel_hi:[1,0,1]
	v_add_u32_e32 v154, s34, v177
	v_mad_i64_i32 v[154:155], s[52:53], v154, s24, v[148:149]
	v_lshl_add_u64 v[162:163], v[154:155], 0, v[150:151]
	v_pk_fma_f32 v[154:155], v[102:103], v[164:165], v[142:143] op_sel_hi:[1,0,1]
	v_pk_fma_f32 v[156:157], v[104:105], v[164:165], v[144:145] op_sel_hi:[1,0,1]
	v_cvt_pk_bf16_f32 v154, v154, v155
	v_pk_fma_f32 v[186:187], v[98:99], v[164:165], v[138:139] op_sel_hi:[1,0,1]
	v_cvt_pk_bf16_f32 v155, v156, v157
	s_nop 0
	v_cvt_pk_bf16_f32 v156, v186, v187
	v_cvt_pk_bf16_f32 v157, v184, v185
	ds_write_b128 v190, v[154:157]
	v_pk_fma_f32 v[184:185], v[68:69], v[164:165], v[132:133] op_sel_hi:[1,0,1]
	s_nop 0
	v_pk_fma_f32 v[154:155], v[70:71], v[164:165], v[134:135] op_sel_hi:[1,0,1]
	v_pk_fma_f32 v[156:157], v[72:73], v[164:165], v[136:137] op_sel_hi:[1,0,1]
	v_cvt_pk_bf16_f32 v154, v154, v155
	v_pk_fma_f32 v[164:165], v[66:67], v[164:165], v[130:131] op_sel_hi:[1,0,1]
	v_cvt_pk_bf16_f32 v155, v156, v157
	s_nop 0
	v_cvt_pk_bf16_f32 v156, v164, v165
	v_cvt_pk_bf16_f32 v157, v184, v185
	ds_write_b128 v190, v[154:157] offset:256
	s_waitcnt lgkmcnt(0)
	s_barrier
	ds_read_b128 v[194:197], v191
	ds_read_b128 v[198:201], v191 offset:1056
	v_add_u32_e32 v193, 0x2a000, v192
	v_add_u32_e32 v202, 0x2bc00, v192
	s_waitcnt lgkmcnt(1)
	global_store_dwordx4 v193, v[194:197], s[98:99] sc0 sc1
	s_waitcnt lgkmcnt(0)
	global_store_dwordx4 v202, v[198:201], s[98:99] sc0 sc1
	s_barrier
	v_pk_fma_f32 v[164:165], v[60:61], v[152:153], v[140:141] op_sel_hi:[1,0,1]
	v_pk_fma_f32 v[184:185], v[58:59], v[152:153], v[138:139] op_sel_hi:[1,0,1]
	v_add_u32_e32 v154, s34, v178
	v_mad_i64_i32 v[154:155], s[52:53], v154, s24, v[148:149]
	v_lshl_add_u64 v[162:163], v[154:155], 0, v[150:151]
	v_pk_fma_f32 v[156:157], v[64:65], v[152:153], v[144:145] op_sel_hi:[1,0,1]
	v_pk_fma_f32 v[154:155], v[62:63], v[152:153], v[142:143] op_sel_hi:[1,0,1]
	s_nop 0
	v_cvt_pk_bf16_f32 v154, v154, v155
	v_cvt_pk_bf16_f32 v155, v156, v157
	v_cvt_pk_bf16_f32 v156, v184, v185
	v_cvt_pk_bf16_f32 v157, v164, v165
	ds_write_b128 v190, v[154:157]
	v_pk_fma_f32 v[164:165], v[28:29], v[152:153], v[132:133] op_sel_hi:[1,0,1]
	v_pk_fma_f32 v[184:185], v[26:27], v[152:153], v[130:131] op_sel_hi:[1,0,1]
	v_pk_fma_f32 v[156:157], v[32:33], v[152:153], v[136:137] op_sel_hi:[1,0,1]
	v_pk_fma_f32 v[154:155], v[30:31], v[152:153], v[134:135] op_sel_hi:[1,0,1]
	v_add_u32_e32 v152, s34, v179
	v_cvt_pk_bf16_f32 v154, v154, v155
	v_cvt_pk_bf16_f32 v155, v156, v157
	v_cvt_pk_bf16_f32 v156, v184, v185
	v_cvt_pk_bf16_f32 v157, v164, v165
	ds_write_b128 v190, v[154:157] offset:256
	s_waitcnt lgkmcnt(0)
	s_barrier
	ds_read_b128 v[194:197], v191
	ds_read_b128 v[198:201], v191 offset:1056
	v_add_u32_e32 v193, 0x70000, v192
	v_add_u32_e32 v202, 0x71c00, v192
	s_waitcnt lgkmcnt(1)
	global_store_dwordx4 v193, v[194:197], s[98:99] sc0 sc1
	s_waitcnt lgkmcnt(0)
	global_store_dwordx4 v202, v[198:201], s[98:99] sc0 sc1
	s_barrier
	v_mov_b32_e32 v162, v153
	v_pk_fma_f32 v[164:165], v[52:53], v[162:163], v[140:141] op_sel_hi:[1,0,1]
	v_mad_i64_i32 v[154:155], s[52:53], v152, s24, v[148:149]
	v_pk_fma_f32 v[152:153], v[54:55], v[162:163], v[142:143] op_sel_hi:[1,0,1]
	v_lshl_add_u64 v[156:157], v[154:155], 0, v[150:151]
	v_pk_fma_f32 v[154:155], v[56:57], v[162:163], v[144:145] op_sel_hi:[1,0,1]
	v_cvt_pk_bf16_f32 v152, v152, v153
	v_pk_fma_f32 v[184:185], v[50:51], v[162:163], v[138:139] op_sel_hi:[1,0,1]
	v_cvt_pk_bf16_f32 v153, v154, v155
	s_nop 0
	v_cvt_pk_bf16_f32 v154, v184, v185
	v_cvt_pk_bf16_f32 v155, v164, v165
	ds_write_b128 v190, v[152:155]
	v_pk_fma_f32 v[164:165], v[20:21], v[162:163], v[132:133] op_sel_hi:[1,0,1]
	s_nop 0
	v_pk_fma_f32 v[152:153], v[22:23], v[162:163], v[134:135] op_sel_hi:[1,0,1]
	v_pk_fma_f32 v[154:155], v[24:25], v[162:163], v[136:137] op_sel_hi:[1,0,1]
	v_cvt_pk_bf16_f32 v152, v152, v153
	v_pk_fma_f32 v[162:163], v[18:19], v[162:163], v[130:131] op_sel_hi:[1,0,1]
	v_cvt_pk_bf16_f32 v153, v154, v155
	s_nop 0
	v_cvt_pk_bf16_f32 v154, v162, v163
	v_cvt_pk_bf16_f32 v155, v164, v165
	ds_write_b128 v190, v[152:155] offset:256
	s_waitcnt lgkmcnt(0)
	s_barrier
; __host__ __device__ __forceinline__ unsigned img_off(unsigned row, unsigned col, unsigned KT) { return (((row >> 8) * KT + (col >> 6)) << 14) + (((row >> 7) & 1u) << 13) + hl_off(row & 127u, col & 63u); }
; __device__ __forceinline__ unsigned cvt_pk_bf16(float lo, float hi) { unsigned r; asm volatile("v_cvt_pk_bf16_f32 %0, %1, %2" : "=v"(r) : "v"(lo), "v"(hi)); return r; }
;     __device__ __forceinline__ void store(const f32x4 (&acc)[2][2][4][2], const Unit& u, int wr, int wc, int fr, int fq, int col0, const f32x4 (&sv)[2][2], const float (&rsv)[2][4]) const {
; #pragma unroll
;         for (int ai = 0; ai < 2; ++ai)
; #pragma unroll
;             for (int m = 0; m < 4; ++m) {
;                 const int row = u.pm * BM + ai * HALF + wr * 64 + m * 16 + fr;
;                 const float rs = rsv[ai][m];
;                 bf16_t* rowp = TILED ? O + img_off((unsigned)row, (unsigned)col0, (unsigned)(ldc >> 6)) : O + (size_t)row * ldc + col0;
; #pragma unroll
;                 for (int bj = 0; bj < 2; ++bj) {
;                     f32x4 v0 = acc[ai][bj][m][0] * rs + sv[bj][0], v1 = acc[ai][bj][m][1] * rs + sv[bj][1];
;                     if (ACT == 1) {
; #pragma unroll
;                         for (int e = 0; e < 4; ++e) { const float a0 = fmaxf(v0[e], 0.f), a1 = fmaxf(v1[e], 0.f); v0[e] = a0 * a0; v1[e] = a1 * a1; }
;                     }
;                     u32x4 w; w.x = cvt_pk_bf16(v0[0], v0[1]); w.y = cvt_pk_bf16(v0[2], v0[3]); w.z = cvt_pk_bf16(v1[0], v1[1]); w.w = cvt_pk_bf16(v1[2], v1[3]);
;                     *(u32x4*)(rowp + (TILED ? bj * 2 * (256 * 64) : bj * HALF)) = w;
;                 }
;             }
;     }
	ds_read_b128 v[194:197], v191
	ds_read_b128 v[198:201], v191 offset:1056
	v_add_u32_e32 v193, 0x7e000, v192
	v_add_u32_e32 v202, 0x7fc00, v192
	s_waitcnt lgkmcnt(1)
	global_store_dwordx4 v193, v[194:197], s[98:99] sc0 sc1
	s_waitcnt lgkmcnt(0)
	global_store_dwordx4 v202, v[198:201], s[98:99] sc0 sc1
	s_barrier
	v_pk_fma_f32 v[162:163], v[44:45], v[146:147], v[140:141] op_sel_hi:[1,0,1]
	v_pk_fma_f32 v[164:165], v[42:43], v[146:147], v[138:139] op_sel_hi:[1,0,1]
	v_add_u32_e32 v152, s34, v180
	v_mad_i64_i32 v[152:153], s[52:53], v152, s24, v[148:149]
	v_lshl_add_u64 v[156:157], v[152:153], 0, v[150:151]
	v_pk_fma_f32 v[154:155], v[48:49], v[146:147], v[144:145] op_sel_hi:[1,0,1]
	v_pk_fma_f32 v[152:153], v[46:47], v[146:147], v[142:143] op_sel_hi:[1,0,1]
	s_nop 0
	v_cvt_pk_bf16_f32 v152, v152, v153
	v_cvt_pk_bf16_f32 v153, v154, v155
	v_cvt_pk_bf16_f32 v154, v164, v165
	v_cvt_pk_bf16_f32 v155, v162, v163
	ds_write_b128 v190, v[152:155]
	v_pk_fma_f32 v[162:163], v[12:13], v[146:147], v[132:133] op_sel_hi:[1,0,1]
	v_pk_fma_f32 v[164:165], v[10:11], v[146:147], v[130:131] op_sel_hi:[1,0,1]
	v_pk_fma_f32 v[154:155], v[16:17], v[146:147], v[136:137] op_sel_hi:[1,0,1]
	v_pk_fma_f32 v[152:153], v[14:15], v[146:147], v[134:135] op_sel_hi:[1,0,1]
	v_add_u32_e32 v146, s34, v181
	v_mad_i64_i32 v[148:149], s[34:35], v146, s24, v[148:149]
	v_mov_b32_e32 v146, v147
	v_cvt_pk_bf16_f32 v152, v152, v153
	v_cvt_pk_bf16_f32 v153, v154, v155
	v_cvt_pk_bf16_f32 v154, v164, v165
	v_cvt_pk_bf16_f32 v155, v162, v163
	ds_write_b128 v190, v[152:155] offset:256
	s_waitcnt lgkmcnt(0)
	s_barrier
	ds_read_b128 v[194:197], v191
	ds_read_b128 v[198:201], v191 offset:1056
	v_add_u32_e32 v193, 0x8c000, v192
	v_add_u32_e32 v202, 0x8dc00, v192
	s_waitcnt lgkmcnt(1)
	global_store_dwordx4 v193, v[194:197], s[98:99] sc0 sc1
	s_waitcnt lgkmcnt(0)
	global_store_dwordx4 v202, v[198:201], s[98:99] sc0 sc1
	s_barrier
	v_lshl_add_u64 v[148:149], v[148:149], 0, v[150:151]
	v_pk_fma_f32 v[144:145], v[40:41], v[146:147], v[144:145] op_sel_hi:[1,0,1]
	v_pk_fma_f32 v[142:143], v[38:39], v[146:147], v[142:143] op_sel_hi:[1,0,1]
	v_pk_fma_f32 v[150:151], v[36:37], v[146:147], v[140:141] op_sel_hi:[1,0,1]
	v_pk_fma_f32 v[140:141], v[34:35], v[146:147], v[138:139] op_sel_hi:[1,0,1]
	v_cvt_pk_bf16_f32 v138, v142, v143
	v_cvt_pk_bf16_f32 v139, v144, v145
	v_pk_fma_f32 v[136:137], v[8:9], v[146:147], v[136:137] op_sel_hi:[1,0,1]
	v_cvt_pk_bf16_f32 v140, v140, v141
	v_cvt_pk_bf16_f32 v141, v150, v151
	ds_write_b128 v190, v[138:141]
	v_pk_fma_f32 v[134:135], v[6:7], v[146:147], v[134:135] op_sel_hi:[1,0,1]
	s_nop 0
	v_pk_fma_f32 v[138:139], v[4:5], v[146:147], v[132:133] op_sel_hi:[1,0,1]
	v_pk_fma_f32 v[132:133], v[2:3], v[146:147], v[130:131] op_sel_hi:[1,0,1]
	v_cvt_pk_bf16_f32 v130, v134, v135
	v_cvt_pk_bf16_f32 v131, v136, v137
	s_nop 0
	v_cvt_pk_bf16_f32 v132, v132, v133
	v_cvt_pk_bf16_f32 v133, v138, v139
	ds_write_b128 v190, v[130:133] offset:256
	s_waitcnt lgkmcnt(0)
	s_barrier
	ds_read_b128 v[194:197], v191
	ds_read_b128 v[198:201], v191 offset:1056
	v_add_u32_e32 v193, 0x9a000, v192
	v_add_u32_e32 v202, 0x9bc00, v192
	s_waitcnt lgkmcnt(1)
	global_store_dwordx4 v193, v[194:197], s[98:99] sc0 sc1
	s_waitcnt lgkmcnt(0)
	global_store_dwordx4 v202, v[198:201], s[98:99] sc0 sc1
	s_barrier
	s_add_u32 s52, s80, 0xffff0000
	s_addc_u32 s53, s81, -1
	s_andn2_b64 vcc, exec, s[56:57]
	s_cbranch_vccz .LBB0_902
